# K-loop: each load segment issues its LDS fragment reads first, scalar/address work and LDS-DMA after
# speedup vs baseline: 1.0007x; 1.0007x over previous
; #define PG8_STAGE(bufoff, gbase, voff) do { _Pragma("unroll") for (int _i = 0; _i < 2; ++_i) \
;         __builtin_amdgcn_global_load_lds((const unsigned*)((const char*)(gbase) + (voff)[_i]), (PG8_LAS unsigned*)(lds + (bufoff) + ldsw + _i * 8192), 16, 0, 0); } while (0)
; #define PG8_LDA(dst, b, h) do { _Pragma("unroll") for (int m = 0; m < 4; ++m) _Pragma("unroll") for (int k = 0; k < 2; ++k) dst[m][k] = *(const PG8_LAS bf16x8*)(lds + PG8_SA(b, h) + aoff + m * 2048 + k * 1024); } while (0)
; #define PG8_LDB(dst, b, h) do { _Pragma("unroll") for (int n = 0; n < 2; ++n) _Pragma("unroll") for (int k = 0; k < 2; ++k) dst[n][k] = *(const PG8_LAS bf16x8*)(lds + PG8_SB(b, h) + boff + n * 2048 + k * 1024); } while (0)
; #define PG8_MMA(ai, bj, At, Bt) do { __builtin_amdgcn_s_setprio(1); _Pragma("unroll") for (int m = 0; m < 4; ++m) _Pragma("unroll") for (int n = 0; n < 2; ++n) _Pragma("unroll") for (int k = 0; k < 2; ++k) \
;         acc[ai][bj][m][n] = __builtin_amdgcn_mfma_f32_16x16x32_bf16(Bt[n][k], At[m][k], acc[ai][bj][m][n], 0, 0, 0); __builtin_amdgcn_s_setprio(0); } while (0)
; #define PG8_WAIT_V(n) asm volatile("s_waitcnt vmcnt(" #n ")" ::: "memory")
; #define PG8_WAIT_L(n) asm volatile("s_waitcnt lgkmcnt(" #n ")" ::: "memory")
; #define PG8_BAR __builtin_amdgcn_s_barrier()
; #define PG8_SCHED __builtin_amdgcn_sched_barrier(0)
; template <class Epi, class Sched, bool ALIGN_EPI = false, bool SP2 = false>
; __device__ __forceinline__ void gemm_phase(PG8_LAS unsigned char* lds, const Gemm g, const Sched& S, const Epi& E) {
;     ...
;             const bool last = (t == nt - 2);
;             const char* a1 = cA + (size_t)(t + 1) * kstep;
;             const char* a2 = last ? nA : cA + (size_t)(t + 2) * kstep; const char* b2 = last ? nB : cB + (size_t)(t + 2) * kstep;
;             const char* a3 = a2 + kstep; const char* b3 = b2 + kstep;
;             if (last && has_next) S.a_ready(nxt);
;             if constexpr (SP2) {
;             PG8_LDB(B0, 0, 0); PG8_LDB(B1, 0, 1); PG8_SCHED; PG8_LDA(At, 0, 0); PG8_STAGE(PG8_SA(1, 1), a1 + hstep, voffA);
;             PG8_WAIT_V(8); PG8_WAIT_L(0); PG8_BAR; PG8_MMA(0, 0, At, B0); PG8_MMA(0, 1, At, B1); PG8_BAR; PG8_SCHED;
;             PG8_LDA(At, 0, 1); PG8_STAGE(PG8_SB(0, 0), b2, voffB); PG8_STAGE(PG8_SB(0, 1), b2 + hstep, voffB); PG8_STAGE(PG8_SA(0, 0), a2, voffA);
.LBB0_441:
	s_add_i32 s66, 0, 0x10000
	s_add_i32 s67, 0, 0x14000
	v_add_u32_e32 v142, s66, v228
	v_add_u32_e32 v158, s67, v228
	ds_read_b128 v[130:133], v142
	ds_read_b128 v[134:137], v142 offset:1024
	ds_read_b128 v[138:141], v142 offset:2048
	ds_read_b128 v[142:145], v142 offset:3072
	ds_read_b128 v[146:149], v158
	ds_read_b128 v[150:153], v158 offset:1024
	ds_read_b128 v[154:157], v158 offset:2048
	ds_read_b128 v[158:161], v158 offset:3072
	v_lshl_add_u64 v[206:207], s[42:43], 0, v[190:191]
	s_add_i32 m0, s93, 0xc000
	ds_read_b128 v[162:165], v230
	ds_read_b128 v[166:169], v230 offset:1024
	ds_read_b128 v[170:173], v230 offset:2048
	ds_read_b128 v[174:177], v230 offset:3072
	ds_read_b128 v[178:181], v230 offset:4096
	ds_read_b128 v[194:197], v230 offset:5120
	ds_read_b128 v[198:201], v230 offset:6144
	ds_read_b128 v[202:205], v230 offset:7168
	s_add_i32 s61, s44, 2
	s_add_u32 s64, s42, 0x80
	s_addc_u32 s45, s43, 0
	s_cmp_eq_u32 s99, s44
	s_cselect_b32 s45, s29, s45
	s_cselect_b32 s44, s28, s64
	s_cselect_b32 s65, s21, s60
	s_cselect_b32 s64, s20, s17
	global_load_lds_dwordx4 v[206:207], off
	v_lshl_add_u64 v[206:207], s[42:43], 0, v[192:193]
	s_add_i32 m0, s93, 0xe000
	s_nop 0
	global_load_lds_dwordx4 v[206:207], off
	s_waitcnt vmcnt(8) lgkmcnt(0)
	s_barrier
	s_setprio 1
	v_mfma_f32_16x16x32_bf16 v[126:129], v[130:133], v[162:165], v[126:129]
	v_mfma_f32_16x16x32_bf16 v[122:125], v[138:141], v[162:165], v[122:125]
	v_mfma_f32_16x16x32_bf16 v[110:113], v[130:133], v[170:173], v[110:113]
	v_mfma_f32_16x16x32_bf16 v[102:105], v[138:141], v[170:173], v[102:105]
	v_mfma_f32_16x16x32_bf16 v[94:97], v[130:133], v[178:181], v[94:97]
	v_mfma_f32_16x16x32_bf16 v[86:89], v[138:141], v[178:181], v[86:89]
	v_mfma_f32_16x16x32_bf16 v[78:81], v[130:133], v[198:201], v[78:81]
	v_mfma_f32_16x16x32_bf16 v[70:73], v[138:141], v[198:201], v[70:73]
	v_mfma_f32_16x16x32_bf16 v[126:129], v[134:137], v[166:169], v[126:129]
	v_mfma_f32_16x16x32_bf16 v[122:125], v[142:145], v[166:169], v[122:125]
	v_mfma_f32_16x16x32_bf16 v[110:113], v[134:137], v[174:177], v[110:113]
	v_mfma_f32_16x16x32_bf16 v[102:105], v[142:145], v[174:177], v[102:105]
	v_mfma_f32_16x16x32_bf16 v[94:97], v[134:137], v[194:197], v[94:97]
	v_mfma_f32_16x16x32_bf16 v[86:89], v[142:145], v[194:197], v[86:89]
	v_mfma_f32_16x16x32_bf16 v[78:81], v[134:137], v[202:205], v[78:81]
	v_mfma_f32_16x16x32_bf16 v[70:73], v[142:145], v[202:205], v[70:73]
	v_mfma_f32_16x16x32_bf16 v[118:121], v[146:149], v[162:165], v[118:121]
	v_mfma_f32_16x16x32_bf16 v[114:117], v[154:157], v[162:165], v[114:117]
	v_mfma_f32_16x16x32_bf16 v[106:109], v[146:149], v[170:173], v[106:109]
	v_mfma_f32_16x16x32_bf16 v[98:101], v[154:157], v[170:173], v[98:101]
	v_mfma_f32_16x16x32_bf16 v[90:93], v[146:149], v[178:181], v[90:93]
	v_mfma_f32_16x16x32_bf16 v[82:85], v[154:157], v[178:181], v[82:85]
	v_mfma_f32_16x16x32_bf16 v[74:77], v[146:149], v[198:201], v[74:77]
	v_mfma_f32_16x16x32_bf16 v[66:69], v[154:157], v[198:201], v[66:69]
	v_mfma_f32_16x16x32_bf16 v[118:121], v[150:153], v[166:169], v[118:121]
	v_mfma_f32_16x16x32_bf16 v[114:117], v[158:161], v[166:169], v[114:117]
	v_mfma_f32_16x16x32_bf16 v[106:109], v[150:153], v[174:177], v[106:109]
	v_mfma_f32_16x16x32_bf16 v[98:101], v[158:161], v[174:177], v[98:101]
	v_mfma_f32_16x16x32_bf16 v[90:93], v[150:153], v[194:197], v[90:93]
	v_mfma_f32_16x16x32_bf16 v[82:85], v[158:161], v[194:197], v[82:85]
	v_mfma_f32_16x16x32_bf16 v[74:77], v[150:153], v[202:205], v[74:77]
	v_mfma_f32_16x16x32_bf16 v[66:69], v[158:161], v[202:205], v[66:69]
	s_setprio 0
	s_barrier
	ds_read_b128 v[162:165], v230 offset:16384
	ds_read_b128 v[166:169], v230 offset:17408
	ds_read_b128 v[170:173], v230 offset:18432
	ds_read_b128 v[174:177], v230 offset:19456
	ds_read_b128 v[178:181], v230 offset:20480
	ds_read_b128 v[194:197], v230 offset:21504
	ds_read_b128 v[198:201], v230 offset:22528
	ds_read_b128 v[202:205], v230 offset:23552
	s_add_i32 s66, s66, s92
	s_mov_b32 m0, s66
	v_lshl_add_u64 v[206:207], s[64:65], 0, v[184:185]
	global_load_lds_dwordx4 v[206:207], off
	s_add_i32 m0, s66, 0x2000
	v_lshl_add_u64 v[208:209], s[64:65], 0, v[188:189]
	s_add_u32 s64, s64, s26
	s_addc_u32 s65, s65, 0
	s_add_i32 s66, s67, s92
	global_load_lds_dwordx4 v[208:209], off
	v_lshl_add_u64 v[210:211], s[64:65], 0, v[184:185]
	s_mov_b32 m0, s66
	v_lshl_add_u64 v[232:233], s[64:65], 0, v[188:189]
	global_load_lds_dwordx4 v[210:211], off
	s_add_i32 m0, s66, 0x2000
	v_lshl_add_u64 v[234:235], s[44:45], 0, v[182:183]
	global_load_lds_dwordx4 v[232:233], off
	s_mov_b32 m0, s93
	v_lshl_add_u64 v[236:237], s[44:45], 0, v[186:187]
	global_load_lds_dwordx4 v[234:235], off
	s_mov_b32 m0, s94
	s_nop 0
	global_load_lds_dwordx4 v[236:237], off
	s_waitcnt vmcnt(8) lgkmcnt(0)
	s_barrier
; #define PG8_STAGE(bufoff, gbase, voff) do { _Pragma("unroll") for (int _i = 0; _i < 2; ++_i) \
;         __builtin_amdgcn_global_load_lds((const unsigned*)((const char*)(gbase) + (voff)[_i]), (PG8_LAS unsigned*)(lds + (bufoff) + ldsw + _i * 8192), 16, 0, 0); } while (0)
; #define PG8_LDA(dst, b, h) do { _Pragma("unroll") for (int m = 0; m < 4; ++m) _Pragma("unroll") for (int k = 0; k < 2; ++k) dst[m][k] = *(const PG8_LAS bf16x8*)(lds + PG8_SA(b, h) + aoff + m * 2048 + k * 1024); } while (0)
; #define PG8_LDB(dst, b, h) do { _Pragma("unroll") for (int n = 0; n < 2; ++n) _Pragma("unroll") for (int k = 0; k < 2; ++k) dst[n][k] = *(const PG8_LAS bf16x8*)(lds + PG8_SB(b, h) + boff + n * 2048 + k * 1024); } while (0)
; #define PG8_MMA(ai, bj, At, Bt) do { __builtin_amdgcn_s_setprio(1); _Pragma("unroll") for (int m = 0; m < 4; ++m) _Pragma("unroll") for (int n = 0; n < 2; ++n) _Pragma("unroll") for (int k = 0; k < 2; ++k) \
;         acc[ai][bj][m][n] = __builtin_amdgcn_mfma_f32_16x16x32_bf16(Bt[n][k], At[m][k], acc[ai][bj][m][n], 0, 0, 0); __builtin_amdgcn_s_setprio(0); } while (0)
; #define PG8_WAIT_V(n) asm volatile("s_waitcnt vmcnt(" #n ")" ::: "memory")
; #define PG8_WAIT_L(n) asm volatile("s_waitcnt lgkmcnt(" #n ")" ::: "memory")
; #define PG8_BAR __builtin_amdgcn_s_barrier()
; #define PG8_SCHED __builtin_amdgcn_sched_barrier(0)
; template <class Epi, class Sched, bool ALIGN_EPI = false, bool SP2 = false>
; __device__ __forceinline__ void gemm_phase(PG8_LAS unsigned char* lds, const Gemm g, const Sched& S, const Epi& E) {
;     ...
;             PG8_WAIT_V(8); PG8_WAIT_L(0); PG8_BAR; PG8_MMA(1, 0, At, B0); PG8_MMA(1, 1, At, B1); PG8_BAR; PG8_SCHED;
;             PG8_LDB(B0, 1, 0); PG8_LDB(B1, 1, 1); PG8_SCHED; PG8_LDA(At, 1, 0); PG8_STAGE(PG8_SA(0, 1), a2 + hstep, voffA);
;             PG8_WAIT_V(8); PG8_WAIT_L(0); PG8_BAR; PG8_MMA(0, 0, At, B0); PG8_MMA(0, 1, At, B1); PG8_BAR; PG8_SCHED;
	s_setprio 1
	v_mfma_f32_16x16x32_bf16 v[62:65], v[130:133], v[162:165], v[62:65]
	v_mfma_f32_16x16x32_bf16 v[54:57], v[138:141], v[162:165], v[54:57]
	v_mfma_f32_16x16x32_bf16 v[46:49], v[130:133], v[170:173], v[46:49]
	v_mfma_f32_16x16x32_bf16 v[38:41], v[138:141], v[170:173], v[38:41]
	v_mfma_f32_16x16x32_bf16 v[30:33], v[130:133], v[178:181], v[30:33]
	v_mfma_f32_16x16x32_bf16 v[22:25], v[138:141], v[178:181], v[22:25]
	v_mfma_f32_16x16x32_bf16 v[14:17], v[130:133], v[198:201], v[14:17]
	v_mfma_f32_16x16x32_bf16 v[6:9], v[138:141], v[198:201], v[6:9]
	v_mfma_f32_16x16x32_bf16 v[62:65], v[134:137], v[166:169], v[62:65]
	v_mfma_f32_16x16x32_bf16 v[54:57], v[142:145], v[166:169], v[54:57]
	v_mfma_f32_16x16x32_bf16 v[46:49], v[134:137], v[174:177], v[46:49]
	v_mfma_f32_16x16x32_bf16 v[38:41], v[142:145], v[174:177], v[38:41]
	v_mfma_f32_16x16x32_bf16 v[30:33], v[134:137], v[194:197], v[30:33]
	v_mfma_f32_16x16x32_bf16 v[22:25], v[142:145], v[194:197], v[22:25]
	v_mfma_f32_16x16x32_bf16 v[14:17], v[134:137], v[202:205], v[14:17]
	v_mfma_f32_16x16x32_bf16 v[6:9], v[142:145], v[202:205], v[6:9]
	v_mfma_f32_16x16x32_bf16 v[58:61], v[146:149], v[162:165], v[58:61]
	v_mfma_f32_16x16x32_bf16 v[50:53], v[154:157], v[162:165], v[50:53]
	v_mfma_f32_16x16x32_bf16 v[42:45], v[146:149], v[170:173], v[42:45]
	v_mfma_f32_16x16x32_bf16 v[34:37], v[154:157], v[170:173], v[34:37]
	v_mfma_f32_16x16x32_bf16 v[26:29], v[146:149], v[178:181], v[26:29]
	v_mfma_f32_16x16x32_bf16 v[18:21], v[154:157], v[178:181], v[18:21]
	v_mfma_f32_16x16x32_bf16 v[10:13], v[146:149], v[198:201], v[10:13]
	v_mfma_f32_16x16x32_bf16 v[2:5], v[154:157], v[198:201], v[2:5]
	v_mfma_f32_16x16x32_bf16 v[58:61], v[150:153], v[166:169], v[58:61]
	v_mfma_f32_16x16x32_bf16 v[50:53], v[158:161], v[166:169], v[50:53]
	v_mfma_f32_16x16x32_bf16 v[42:45], v[150:153], v[174:177], v[42:45]
	v_mfma_f32_16x16x32_bf16 v[34:37], v[158:161], v[174:177], v[34:37]
	v_mfma_f32_16x16x32_bf16 v[26:29], v[150:153], v[194:197], v[26:29]
	v_mfma_f32_16x16x32_bf16 v[18:21], v[158:161], v[194:197], v[18:21]
	v_mfma_f32_16x16x32_bf16 v[10:13], v[150:153], v[202:205], v[10:13]
	v_mfma_f32_16x16x32_bf16 v[2:5], v[158:161], v[202:205], v[2:5]
	s_setprio 0
	s_barrier
	ds_read_b128 v[162:165], v230 offset:32768
	ds_read_b128 v[166:169], v230 offset:33792
	ds_read_b128 v[170:173], v230 offset:34816
	ds_read_b128 v[174:177], v230 offset:35840
	ds_read_b128 v[178:181], v230 offset:36864
	ds_read_b128 v[194:197], v230 offset:37888
	ds_read_b128 v[198:201], v230 offset:38912
	ds_read_b128 v[202:205], v230 offset:39936
	s_add_i32 s64, 0, 0x18000
	s_add_i32 s65, 0, 0x1c000
	v_add_u32_e32 v142, s64, v228
	v_add_u32_e32 v158, s65, v228
	ds_read_b128 v[130:133], v142
	ds_read_b128 v[134:137], v142 offset:1024
	ds_read_b128 v[138:141], v142 offset:2048
	ds_read_b128 v[142:145], v142 offset:3072
	ds_read_b128 v[146:149], v158
	ds_read_b128 v[150:153], v158 offset:1024
	ds_read_b128 v[154:157], v158 offset:2048
	ds_read_b128 v[158:161], v158 offset:3072
	s_add_u32 s44, s44, s26
	s_addc_u32 s45, s45, 0
	s_mov_b32 m0, s95
	v_lshl_add_u64 v[238:239], s[44:45], 0, v[182:183]
	global_load_lds_dwordx4 v[238:239], off
	v_lshl_add_u64 v[238:239], s[44:45], 0, v[186:187]
	s_mov_b32 m0, s96
	s_nop 0
	global_load_lds_dwordx4 v[238:239], off
	s_waitcnt vmcnt(8) lgkmcnt(0)
	s_barrier
	s_setprio 1
	v_mfma_f32_16x16x32_bf16 v[126:129], v[130:133], v[162:165], v[126:129]
	v_mfma_f32_16x16x32_bf16 v[122:125], v[138:141], v[162:165], v[122:125]
	v_mfma_f32_16x16x32_bf16 v[110:113], v[130:133], v[170:173], v[110:113]
	v_mfma_f32_16x16x32_bf16 v[102:105], v[138:141], v[170:173], v[102:105]
	v_mfma_f32_16x16x32_bf16 v[94:97], v[130:133], v[178:181], v[94:97]
	v_mfma_f32_16x16x32_bf16 v[86:89], v[138:141], v[178:181], v[86:89]
	v_mfma_f32_16x16x32_bf16 v[78:81], v[130:133], v[198:201], v[78:81]
	v_mfma_f32_16x16x32_bf16 v[70:73], v[138:141], v[198:201], v[70:73]
	v_mfma_f32_16x16x32_bf16 v[126:129], v[134:137], v[166:169], v[126:129]
	v_mfma_f32_16x16x32_bf16 v[122:125], v[142:145], v[166:169], v[122:125]
	v_mfma_f32_16x16x32_bf16 v[110:113], v[134:137], v[174:177], v[110:113]
	v_mfma_f32_16x16x32_bf16 v[102:105], v[142:145], v[174:177], v[102:105]
	v_mfma_f32_16x16x32_bf16 v[94:97], v[134:137], v[194:197], v[94:97]
	v_mfma_f32_16x16x32_bf16 v[86:89], v[142:145], v[194:197], v[86:89]
	v_mfma_f32_16x16x32_bf16 v[78:81], v[134:137], v[202:205], v[78:81]
	v_mfma_f32_16x16x32_bf16 v[70:73], v[142:145], v[202:205], v[70:73]
	v_mfma_f32_16x16x32_bf16 v[118:121], v[146:149], v[162:165], v[118:121]
	v_mfma_f32_16x16x32_bf16 v[114:117], v[154:157], v[162:165], v[114:117]
	v_mfma_f32_16x16x32_bf16 v[106:109], v[146:149], v[170:173], v[106:109]
	v_mfma_f32_16x16x32_bf16 v[98:101], v[154:157], v[170:173], v[98:101]
	v_mfma_f32_16x16x32_bf16 v[90:93], v[146:149], v[178:181], v[90:93]
	v_mfma_f32_16x16x32_bf16 v[82:85], v[154:157], v[178:181], v[82:85]
	v_mfma_f32_16x16x32_bf16 v[74:77], v[146:149], v[198:201], v[74:77]
	v_mfma_f32_16x16x32_bf16 v[66:69], v[154:157], v[198:201], v[66:69]
	v_mfma_f32_16x16x32_bf16 v[118:121], v[150:153], v[166:169], v[118:121]
	v_mfma_f32_16x16x32_bf16 v[114:117], v[158:161], v[166:169], v[114:117]
	v_mfma_f32_16x16x32_bf16 v[106:109], v[150:153], v[174:177], v[106:109]
	v_mfma_f32_16x16x32_bf16 v[98:101], v[158:161], v[174:177], v[98:101]
	v_mfma_f32_16x16x32_bf16 v[90:93], v[150:153], v[194:197], v[90:93]
	v_mfma_f32_16x16x32_bf16 v[82:85], v[158:161], v[194:197], v[82:85]
	v_mfma_f32_16x16x32_bf16 v[74:77], v[150:153], v[202:205], v[74:77]
	v_mfma_f32_16x16x32_bf16 v[66:69], v[158:161], v[202:205], v[66:69]
	s_setprio 0
	s_barrier
; #define PG8_STAGE(bufoff, gbase, voff) do { _Pragma("unroll") for (int _i = 0; _i < 2; ++_i) \
;         __builtin_amdgcn_global_load_lds((const unsigned*)((const char*)(gbase) + (voff)[_i]), (PG8_LAS unsigned*)(lds + (bufoff) + ldsw + _i * 8192), 16, 0, 0); } while (0)
; #define PG8_LDA(dst, b, h) do { _Pragma("unroll") for (int m = 0; m < 4; ++m) _Pragma("unroll") for (int k = 0; k < 2; ++k) dst[m][k] = *(const PG8_LAS bf16x8*)(lds + PG8_SA(b, h) + aoff + m * 2048 + k * 1024); } while (0)
; #define PG8_MMA(ai, bj, At, Bt) do { __builtin_amdgcn_s_setprio(1); _Pragma("unroll") for (int m = 0; m < 4; ++m) _Pragma("unroll") for (int n = 0; n < 2; ++n) _Pragma("unroll") for (int k = 0; k < 2; ++k) \
;         acc[ai][bj][m][n] = __builtin_amdgcn_mfma_f32_16x16x32_bf16(Bt[n][k], At[m][k], acc[ai][bj][m][n], 0, 0, 0); __builtin_amdgcn_s_setprio(0); } while (0)
; #define PG8_WAIT_V(n) asm volatile("s_waitcnt vmcnt(" #n ")" ::: "memory")
; #define PG8_WAIT_L(n) asm volatile("s_waitcnt lgkmcnt(" #n ")" ::: "memory")
; #define PG8_BAR __builtin_amdgcn_s_barrier()
; #define PG8_SCHED __builtin_amdgcn_sched_barrier(0)
; template <class Epi, class Sched, bool ALIGN_EPI = false, bool SP2 = false>
; __device__ __forceinline__ void gemm_phase(PG8_LAS unsigned char* lds, const Gemm g, const Sched& S, const Epi& E) {
;     ...
;             PG8_LDA(At, 1, 1); PG8_STAGE(PG8_SB(1, 0), b3, voffB); PG8_STAGE(PG8_SB(1, 1), b3 + hstep, voffB); PG8_STAGE(PG8_SA(1, 0), a3, voffA);
;             PG8_WAIT_V(8); PG8_WAIT_L(0); PG8_BAR; PG8_MMA(1, 0, At, B0); PG8_MMA(1, 1, At, B1); PG8_BAR; PG8_SCHED;
;     ...
;         if constexpr (ALIGN_EPI) { if (wr == 0) PG8_BAR; }
;         if constexpr (!Epi::AFTER_DRAIN) { E(acc, cur, wr, wc, fr, fq); S.done(cur); }
	ds_read_b128 v[162:165], v230 offset:49152
	ds_read_b128 v[166:169], v230 offset:50176
	ds_read_b128 v[170:173], v230 offset:51200
	ds_read_b128 v[174:177], v230 offset:52224
	ds_read_b128 v[178:181], v230 offset:53248
	ds_read_b128 v[194:197], v230 offset:54272
	ds_read_b128 v[198:201], v230 offset:55296
	ds_read_b128 v[202:205], v230 offset:56320
	s_add_i32 s44, s64, s92
	s_mov_b32 m0, s44
	v_lshl_add_u64 v[206:207], v[206:207], 0, s[34:35]
	global_load_lds_dwordx4 v[206:207], off
	v_lshl_add_u64 v[206:207], v[208:209], 0, s[34:35]
	s_add_i32 m0, s44, 0x2000
	s_add_i32 s44, s65, s92
	global_load_lds_dwordx4 v[206:207], off
	v_lshl_add_u64 v[206:207], v[210:211], 0, s[34:35]
	s_mov_b32 m0, s44
	s_nop 0
	global_load_lds_dwordx4 v[206:207], off
	v_lshl_add_u64 v[206:207], v[232:233], 0, s[34:35]
	s_add_i32 m0, s44, 0x2000
	s_nop 0
	global_load_lds_dwordx4 v[206:207], off
	v_lshl_add_u64 v[206:207], v[234:235], 0, s[34:35]
	s_mov_b32 m0, s97
	s_nop 0
	global_load_lds_dwordx4 v[206:207], off
	v_lshl_add_u64 v[206:207], v[236:237], 0, s[34:35]
	s_mov_b32 m0, s98
	s_nop 0
	global_load_lds_dwordx4 v[206:207], off
	s_add_u32 s42, s42, 0x100
	s_addc_u32 s43, s43, 0
	s_add_u32 s17, s17, 0x100
	s_addc_u32 s60, s60, 0
	s_cmp_ge_u32 s61, s4
	s_mov_b32 s44, s61
	s_waitcnt vmcnt(8) lgkmcnt(0)
	s_barrier
	s_setprio 1
	v_mfma_f32_16x16x32_bf16 v[62:65], v[130:133], v[162:165], v[62:65]
	v_mfma_f32_16x16x32_bf16 v[54:57], v[138:141], v[162:165], v[54:57]
	v_mfma_f32_16x16x32_bf16 v[46:49], v[130:133], v[170:173], v[46:49]
	v_mfma_f32_16x16x32_bf16 v[38:41], v[138:141], v[170:173], v[38:41]
	v_mfma_f32_16x16x32_bf16 v[30:33], v[130:133], v[178:181], v[30:33]
	v_mfma_f32_16x16x32_bf16 v[22:25], v[138:141], v[178:181], v[22:25]
	v_mfma_f32_16x16x32_bf16 v[14:17], v[130:133], v[198:201], v[14:17]
	v_mfma_f32_16x16x32_bf16 v[6:9], v[138:141], v[198:201], v[6:9]
	v_mfma_f32_16x16x32_bf16 v[62:65], v[134:137], v[166:169], v[62:65]
	v_mfma_f32_16x16x32_bf16 v[54:57], v[142:145], v[166:169], v[54:57]
	v_mfma_f32_16x16x32_bf16 v[46:49], v[134:137], v[174:177], v[46:49]
	v_mfma_f32_16x16x32_bf16 v[38:41], v[142:145], v[174:177], v[38:41]
	v_mfma_f32_16x16x32_bf16 v[30:33], v[134:137], v[194:197], v[30:33]
	v_mfma_f32_16x16x32_bf16 v[22:25], v[142:145], v[194:197], v[22:25]
	v_mfma_f32_16x16x32_bf16 v[14:17], v[134:137], v[202:205], v[14:17]
	v_mfma_f32_16x16x32_bf16 v[6:9], v[142:145], v[202:205], v[6:9]
	v_mfma_f32_16x16x32_bf16 v[58:61], v[146:149], v[162:165], v[58:61]
	v_mfma_f32_16x16x32_bf16 v[50:53], v[154:157], v[162:165], v[50:53]
	v_mfma_f32_16x16x32_bf16 v[42:45], v[146:149], v[170:173], v[42:45]
	v_mfma_f32_16x16x32_bf16 v[34:37], v[154:157], v[170:173], v[34:37]
	v_mfma_f32_16x16x32_bf16 v[26:29], v[146:149], v[178:181], v[26:29]
	v_mfma_f32_16x16x32_bf16 v[18:21], v[154:157], v[178:181], v[18:21]
	v_mfma_f32_16x16x32_bf16 v[10:13], v[146:149], v[198:201], v[10:13]
	v_mfma_f32_16x16x32_bf16 v[2:5], v[154:157], v[198:201], v[2:5]
	v_mfma_f32_16x16x32_bf16 v[58:61], v[150:153], v[166:169], v[58:61]
	v_mfma_f32_16x16x32_bf16 v[50:53], v[158:161], v[166:169], v[50:53]
	v_mfma_f32_16x16x32_bf16 v[42:45], v[150:153], v[174:177], v[42:45]
	v_mfma_f32_16x16x32_bf16 v[34:37], v[158:161], v[174:177], v[34:37]
	v_mfma_f32_16x16x32_bf16 v[26:29], v[150:153], v[194:197], v[26:29]
	v_mfma_f32_16x16x32_bf16 v[18:21], v[158:161], v[194:197], v[18:21]
	v_mfma_f32_16x16x32_bf16 v[10:13], v[150:153], v[202:205], v[10:13]
	v_mfma_f32_16x16x32_bf16 v[2:5], v[158:161], v[202:205], v[2:5]
	s_setprio 0
	s_barrier
	s_cbranch_scc0 .LBB0_441
	s_and_b64 vcc, exec, s[36:37]
	s_cbranch_vccz .LBB0_445
	s_barrier
	s_cmp_lt_i32 s0, 2
	s_mov_b64 s[42:43], -1
	s_cbranch_scc0 .LBB0_446
